# next layer's w_in conversion moved from the start of P5 (all workgroups) into the mixer workgroups' slack at the end of P4 (scan is the critical path there)
# speedup vs baseline: 1.0024x; 1.0024x over previous
.LBB0_564:
	s_cmp_lt_u32 s74, 32
	s_cbranch_scc1 .Lwin_skip
	v_readlane_b32 s12, v255, 31
	s_cmp_lg_u32 s12, 0
	s_cbranch_scc1 .Lwin_skip
	s_sub_u32 s1, s74, 32
	s_movk_i32 s0, 0xe0
	s_mov_b32 s6, 0x1c000
	v_readfirstlane_b32 s2, v211
	v_mov_b32_e32 v10, v211
	v_lshl_add_u32 v0, s1, 9, v10
	s_mov_b64 s[8:9], s[92:93]
	s_movk_i32 s52, 0x1fff
	s_add_i32 s3, s12, 1
	s_lshl_b32 s7, s1, 3
	s_ashr_i32 s4, s2, 6
	v_readlane_b32 s16, v254, 10
	s_add_i32 s2, s7, s4
	s_mul_hi_i32 s7, s3, 0xc08000
	s_mul_i32 s3, s3, 0xc08000
	v_readlane_b32 s22, v254, 16
	v_readlane_b32 s23, v254, 17
	s_add_u32 s14, s22, s3
	s_addc_u32 s15, s23, s7
	s_cmpk_gt_i32 s2, 0x5ff
	v_readlane_b32 s17, v254, 11
	v_readlane_b32 s18, v254, 12
	v_readlane_b32 s19, v254, 13
	v_readlane_b32 s20, v254, 14
	v_readlane_b32 s21, v254, 15
	v_readlane_b32 s24, v254, 18
	v_readlane_b32 s25, v254, 19
	v_readlane_b32 s26, v254, 20
	v_readlane_b32 s27, v254, 21
	v_readlane_b32 s28, v254, 22
	v_readlane_b32 s29, v254, 23
	v_readlane_b32 s30, v254, 24
	v_readlane_b32 s31, v254, 25
	s_cbranch_scc1 .Lwin_621
	s_mulk_i32 s4, 0x2100
	v_lshlrev_b32_e32 v2, 2, v10
	v_lshlrev_b32_e32 v4, 3, v10
	s_add_i32 s4, s4, 0
	v_and_b32_e32 v196, 0x7c, v2
	v_and_b32_e32 v4, 56, v4
	v_bfe_u32 v1, v10, 5, 1
	v_lshl_add_u64 v[2:3], s[14:15], 0, v[196:197]
	v_add_u32_e32 v6, s4, v196
	v_bfe_u32 v11, v10, 3, 3
	v_lshlrev_b32_e32 v196, 1, v4
	v_mul_u32_u24_e32 v7, 0x84, v1
	v_mul_u32_u24_e32 v8, 0x84, v4
	v_lshl_add_u64 v[4:5], s[8:9], 0, v[196:197]
	s_mov_b64 s[16:17], 0x200000
	v_lshlrev_b32_e32 v9, 2, v11
	s_lshl_b32 s3, s0, 3
	v_lshl_add_u64 v[4:5], v[4:5], 0, s[16:17]
	v_add3_u32 v12, s4, v8, v9
	s_lshl_b32 s4, s2, 5
	s_lshl_b32 s7, s0, 8
	v_add_u32_e32 v13, v6, v7

.Lwin_629:
	s_or_b64 exec, exec, s[16:17]
.Lwin_skip:
	s_sub_u32 s98, s74, 32
	s_cmp_lt_u32 s98, 8
	s_cbranch_scc0 .Lp4_nowb
	v_readlane_b32 s98, v211, 0
	s_cmp_lt_u32 s98, 64
	s_cbranch_scc0 .Lp4_nowb
	s_waitcnt vmcnt(0)
	buffer_wbl2 sc1

.LBB0_616:
	s_or_b64 exec, exec, s[6:7]
	s_waitcnt vmcnt(18)
	v_mov_b32_e32 v10, v211
	s_mov_b32 s1, s74
	s_mov_b32 s0, s94
	v_readlane_b32 s3, v255, 31
	s_waitcnt lgkmcnt(0)
	s_barrier
	s_lshl_b32 s6, s0, 9
	s_mov_b32 s12, s3
	v_readfirstlane_b32 s2, v10
	s_waitcnt vmcnt(16)
	v_lshl_add_u32 v0, s1, 9, v10
	s_mov_b64 s[8:9], s[92:93]
	s_cmp_lt_i32 s12, 1
	s_mov_b32 s2, 0x80000
	v_cmp_gt_i32_e32 vcc, s2, v0
	s_and_saveexec_b64 s[14:15], vcc
	s_cbranch_execnz .LBB0_630
	s_branch .LBB0_634
